# r1 first-tile prologue: five load/vmcnt(0)/shift round trips replaced by d16_hi loads into pre-zeroed registers
# baseline (speedup 1.0000x reference)
.LBB0_393:
	s_or_b64 exec, exec, s[0:1]
	v_or_b32_e32 v72, 1, v4
	v_cmp_le_i32_e32 vcc, s31, v72
	v_cmp_gt_i32_e64 s[4:5], s33, v72
	s_and_b64 s[4:5], vcc, s[4:5]
	s_and_saveexec_b64 s[0:1], s[4:5]
	s_cbranch_execz .LBB0_395
	v_lshlrev_b64 v[14:15], 10, v[72:73]
	v_lshl_add_u64 v[14:15], v[0:1], 0, v[14:15]
	global_load_short_d16_hi v6, v[14:15], off

.LBB0_397:
	s_or_b64 exec, exec, s[0:1]
	v_or_b32_e32 v72, 1, v2
	v_cmp_le_i32_e32 vcc, s31, v72
	v_cmp_gt_i32_e64 s[4:5], s33, v72
	s_and_b64 s[4:5], vcc, s[4:5]
	s_and_saveexec_b64 s[0:1], s[4:5]
	s_cbranch_execz .LBB0_399
	v_lshlrev_b64 v[8:9], 10, v[72:73]
	v_lshl_add_u64 v[8:9], v[0:1], 0, v[8:9]
	global_load_short_d16_hi v4, v[8:9], off

.LBB0_401:
	s_or_b64 exec, exec, s[0:1]
	v_or_b32_e32 v72, 3, v2
	v_cmp_le_i32_e32 vcc, s31, v72
	v_cmp_gt_i32_e64 s[4:5], s33, v72
	s_and_b64 s[4:5], vcc, s[4:5]
	s_and_saveexec_b64 s[0:1], s[4:5]
	s_cbranch_execz .LBB0_403
	v_lshlrev_b64 v[14:15], 10, v[72:73]
	v_lshl_add_u64 v[14:15], v[0:1], 0, v[14:15]
	global_load_short_d16_hi v8, v[14:15], off

.LBB0_405:
	s_or_b64 exec, exec, s[0:1]
	v_or_b32_e32 v72, 5, v2
	v_cmp_le_i32_e32 vcc, s31, v72
	v_cmp_gt_i32_e64 s[4:5], s33, v72
	s_and_b64 s[4:5], vcc, s[4:5]
	s_and_saveexec_b64 s[0:1], s[4:5]
	s_cbranch_execz .LBB0_407
	v_lshlrev_b64 v[14:15], 10, v[72:73]
	v_lshl_add_u64 v[14:15], v[0:1], 0, v[14:15]
	global_load_short_d16_hi v10, v[14:15], off

.LBB0_409:
	s_or_b64 exec, exec, s[0:1]
	v_or_b32_e32 v72, 7, v2
	v_cmp_le_i32_e32 vcc, s31, v72
	v_cmp_gt_i32_e64 s[4:5], s33, v72
	s_and_b64 s[4:5], vcc, s[4:5]
	s_and_saveexec_b64 s[0:1], s[4:5]
	s_cbranch_execz .LBB0_411
	v_lshlrev_b64 v[14:15], 10, v[72:73]
	v_lshl_add_u64 v[14:15], v[0:1], 0, v[14:15]
	global_load_short_d16_hi v12, v[14:15], off
